# P3 loop: four p0 exponentials issued ahead of the p1 chain; three per p1-chain gap (at the 6-VALU/MFMA ceiling)
# baseline (speedup 1.0000x reference)
.LBB0_325:
	s_waitcnt lgkmcnt(4)
	v_mfma_f32_32x32x16_bf16 v[96:111], v[80:83], v[144:147], v[64:79]
	v_mfma_f32_32x32x16_bf16 v[96:111], v[202:205], v[140:143], v[96:111]
	s_add_i32 s4, s100, 64
	v_cvt_f32_i32_e32 v156, s4
	v_add_f32_e32 v156, v255, v156
	v_fma_f32 v254, v208, v156, -v207
	s_nop 0
	v_mfma_f32_32x32x16_bf16 v[96:111], v[194:197], v[136:139], v[96:111]
	v_mov_b32_e32 v64, v254
	v_fmamk_f32 v65, v208, 0x3f800000, v254
	v_fmamk_f32 v66, v208, 0x40000000, v254
	v_fmamk_f32 v67, v208, 0x40400000, v254
	v_fmamk_f32 v68, v208, 0x41000000, v254
	v_fmamk_f32 v69, v208, 0x41100000, v254
	v_fmamk_f32 v70, v208, 0x41200000, v254
	v_fmamk_f32 v71, v208, 0x41300000, v254
	v_mfma_f32_32x32x16_bf16 v[96:111], v[186:189], v[132:135], v[96:111]
	v_fmamk_f32 v72, v208, 0x41800000, v254
	v_fmamk_f32 v73, v208, 0x41880000, v254
	v_fmamk_f32 v74, v208, 0x41900000, v254
	v_fmamk_f32 v75, v208, 0x41980000, v254
	v_fmamk_f32 v76, v208, 0x41c00000, v254
	v_fmamk_f32 v77, v208, 0x41c80000, v254
	v_fmamk_f32 v78, v208, 0x41d00000, v254
	v_fmamk_f32 v79, v208, 0x41d80000, v254
	s_add_i32 s3, s79, 0xfffe8000
	s_and_b32 s3, s3, 0x18000
	v_add_u32_e32 v158, s3, v235
	v_add_u32_e32 v159, s3, v239
	v_add_u32_e32 v160, s3, v236
	v_add_u32_e32 v161, s3, v234
	ds_read_b64_tr_b16 v[182:183], v158 offset:32768
	ds_read_b64_tr_b16 v[184:185], v158 offset:34816
	ds_read_b64_tr_b16 v[178:179], v159 offset:32768
	ds_read_b64_tr_b16 v[180:181], v159 offset:34816
	ds_read_b64_tr_b16 v[148:149], v160 offset:32768
	ds_read_b64_tr_b16 v[150:151], v160 offset:34816
	ds_read_b64_tr_b16 v[152:153], v161 offset:32768
	ds_read_b64_tr_b16 v[154:155], v161 offset:34816
	v_exp_f32_e32 v96, v96
	v_exp_f32_e32 v97, v97
	v_exp_f32_e32 v98, v98
	v_exp_f32_e32 v99, v99
	s_waitcnt lgkmcnt(8)
	v_mfma_f32_32x32x16_bf16 v[80:95], v[198:201], v[144:147], v[64:79]
	v_exp_f32_e32 v100, v100
	v_exp_f32_e32 v101, v101
	v_exp_f32_e32 v102, v102
	v_mfma_f32_32x32x16_bf16 v[80:95], v[190:193], v[140:143], v[80:95]
	v_exp_f32_e32 v103, v103
	v_exp_f32_e32 v104, v104
	v_exp_f32_e32 v105, v105
	v_mfma_f32_32x32x16_bf16 v[80:95], v[246:249], v[136:139], v[80:95]
	v_exp_f32_e32 v106, v106
	v_exp_f32_e32 v107, v107
	v_exp_f32_e32 v108, v108
	v_mfma_f32_32x32x16_bf16 v[80:95], v[250:253], v[132:135], v[80:95]
	v_exp_f32_e32 v109, v109
	v_exp_f32_e32 v110, v110
	v_exp_f32_e32 v111, v111
	s_nop 4
	s_cmp_le_i32 s72, s101
	s_cbranch_scc0 .Lmask_blk
